# P0 norm: layer norm gain kept in registers for the phase (12 instead of 16 row loads per token row)
# speedup vs baseline: 1.0094x; 1.0029x over previous
; DEV void norm_item(const Params& p, int l, int g, int item, int tid) {
;   const int wid = tid >> 6, lane = tid & 63;
;   const int r = item * 8 + wid;
;   const int bl = r / NTOK, j = r % NTOK, b = g * G + bl;
;   const float* src;
;   int mrow;
;   if (j < NCTX) {
;     src = (l == 0 ? p.ctx : p.hctx) + ((long)b * NCTX + j) * D;
;     mrow = 32;
;   } else {
;     src = (l == 0 ? p.x : p.out) + ((long)b * SEQ + (j - NCTX)) * D;
;     mrow = b;
;   }
;   const float* md = p.mod + ((long)l * 33 + mrow) * 3072;
;   const float* ng = p.norm_g + l * D;
;   float4 v[4];
;   float ss = 0.f;
; #pragma unroll
;   for (int i = 0; i < 4; ++i) {
;     v[i] = *(const float4*)(src + i * 256 + lane * 4);
;     ss += v[i].x * v[i].x + v[i].y * v[i].y + v[i].z * v[i].z + v[i].w * v[i].w;
;   }
;   ss = wsum(ss, lane);
;   const float rstd = rsqrtf(ss * (1.f / D) + 1e-6f);
; #pragma unroll
;   for (int i = 0; i < 4; ++i) {
;     int col = i * 256 + lane * 4;
;     float4 gg = *(const float4*)(ng + col);
;     float4 sh = *(const float4*)(md + col);
;     float4 sc = *(const float4*)(md + 1024 + col);
.LBB0_104:
	s_cmp_eq_u32 s14, 0
	s_cselect_b64 s[6:7], -1, 0
	v_writelane_b32 v255, s6, 38
	s_lshl_b32 s24, s14, 10
	s_nop 0
	v_writelane_b32 v255, s7, 39
	v_readlane_b32 s6, v253, 23
	v_readlane_b32 s7, v253, 24
	s_andn2_b64 vcc, exec, s[6:7]
	s_cbranch_vccnz .LBB0_111
	v_readlane_b32 s6, v255, 38
	v_readlane_b32 s7, v255, 39
	s_and_b64 s[6:7], s[6:7], exec
	s_cselect_b32 s6, 0, 0x98
	s_cselect_b32 s8, 16, 0xe0
	s_lshl_b64 s[12:13], s[24:25], 2
	v_readlane_b32 s16, v255, 15
	v_readlane_b32 s17, v255, 16
	s_add_u32 s16, s16, s12
	s_mov_b32 s7, s25
	s_mov_b32 s9, s25
	s_mul_i32 s10, s14, 33
	s_mov_b32 s11, s25
	s_addc_u32 s17, s17, s13
	v_readlane_b32 s15, v254, 36
	s_mov_b32 s18, s75
	v_readlane_b32 s12, v253, 0
	v_readlane_b32 s13, v253, 1
	v_lshrrev_b32_e32 v0, 6, v197
	s_load_dwordx2 s[56:57], s[12:13], s6
	s_load_dwordx2 s[58:59], s[12:13], s8
	v_and_b32_e32 v1, 63, v197
	v_readfirstlane_b32 s60, v0
	v_lshlrev_b32_e32 v156, 4, v1
	v_lshlrev_b32_e32 v50, 3, v1
	v_lshlrev_b32_e32 v51, 2, v197
	v_xor_b32_e32 v64, 0x80, v51
	v_and_b32_e32 v64, 0xfc, v64
	v_xor_b32_e32 v65, 0x40, v51
	v_and_b32_e32 v65, 0xfc, v65
	v_xor_b32_e32 v66, 0x20, v51
	v_and_b32_e32 v66, 0xfc, v66
	v_xor_b32_e32 v67, 0x10, v51
	v_and_b32_e32 v67, 0xfc, v67
	v_xor_b32_e32 v68, 0x8, v51
	v_and_b32_e32 v68, 0xfc, v68
	v_xor_b32_e32 v69, 0x4, v51
	v_and_b32_e32 v69, 0xfc, v69
	s_waitcnt lgkmcnt(0)
	s_mov_b32 s46, 0x800000
	s_mov_b64 s[48:49], s[56:57]
	global_load_dwordx4 v[96:99], v156, s[16:17]
	global_load_dwordx4 v[100:103], v156, s[16:17] offset:1024
	global_load_dwordx4 v[104:107], v156, s[16:17] offset:2048
	global_load_dwordx4 v[108:111], v156, s[16:17] offset:3072
	s_mov_b32 s44, 0
	s_cmpk_gt_i32 s18, 0x8ff
	s_cbranch_scc1 .Lp0_skipA_0
	s_mov_b32 s44, 1
	s_add_i32 s19, s15, s60
	s_mul_hi_u32 s32, s19, 0x38e38e39
	s_lshr_b32 s32, s32, 9
	s_mul_i32 s11, s32, 0x900
	s_sub_i32 s61, s19, s11
	s_lshl_b32 s12, s19, 11
	s_add_u32 s12, s86, s12
	s_addc_u32 s13, s87, 0
	v_readlane_b32 s19, v255, 29
	s_nop 0
	s_add_i32 s32, s32, s19
	s_add_i32 s19, s61, 0xffffff00
	s_cmp_lt_u32 s61, 0x100
	s_cselect_b32 s62, s58, s48
	s_cselect_b32 s63, s59, s49
	s_cselect_b32 s11, 20, 23
	s_cselect_b32 s79, 32, s32
	s_cselect_b32 s19, s61, s19
	s_lshl_b32 s32, s32, s11
	s_lshl_b32 s19, s19, 12
	s_add_u32 s32, s32, s19
	s_add_u32 s62, s62, s32
	s_addc_u32 s63, s63, 0
	s_add_i32 s79, s79, s10
	s_mul_i32 s79, s79, 0x3000
	v_readlane_b32 s19, v253, 21
	v_readlane_b32 s32, v253, 22
	s_nop 0
	s_add_u32 s6, s19, s79
	s_addc_u32 s7, s32, 0
	s_add_u32 s8, s6, 0x1000
	s_addc_u32 s9, s7, 0
	global_load_dwordx4 v[4:7], v156, s[62:63]
	global_load_dwordx4 v[8:11], v156, s[62:63] offset:1024
	global_load_dwordx4 v[12:15], v156, s[62:63] offset:2048
	global_load_dwordx4 v[16:19], v156, s[62:63] offset:3072
	global_load_dwordx4 v[200:203], v156, s[8:9]
	global_load_dwordx4 v[174:177], v156, s[6:7]
	global_load_dwordx4 v[204:207], v156, s[8:9] offset:1024
	global_load_dwordx4 v[178:181], v156, s[6:7] offset:1024
	global_load_dwordx4 v[208:211], v156, s[8:9] offset:2048
	global_load_dwordx4 v[182:185], v156, s[6:7] offset:2048
	global_load_dwordx4 v[212:215], v156, s[8:9] offset:3072
	global_load_dwordx4 v[186:189], v156, s[6:7] offset:3072
	v_readlane_b32 s19, v253, 2
	v_readlane_b32 s32, v255, 27
	s_nop 0
	s_add_i32 s18, s18, s19
	s_add_i32 s15, s15, s32
.Lp0_skipA_0:
	s_mov_b32 s45, 0
	s_cmpk_gt_i32 s18, 0x8ff
	s_cbranch_scc1 .Lp0_skipB_1
	s_mov_b32 s45, 1
	s_add_i32 s19, s15, s60
	s_mul_hi_u32 s32, s19, 0x38e38e39
	s_lshr_b32 s32, s32, 9
	s_mul_i32 s11, s32, 0x900
	s_sub_i32 s61, s19, s11
	s_lshl_b32 s54, s19, 11
	s_add_u32 s54, s86, s54
	s_addc_u32 s55, s87, 0
	v_readlane_b32 s19, v255, 29
	s_nop 0
	s_add_i32 s32, s32, s19
	s_add_i32 s19, s61, 0xffffff00
	s_cmp_lt_u32 s61, 0x100
	s_cselect_b32 s56, s58, s48
	s_cselect_b32 s57, s59, s49
	s_cselect_b32 s11, 20, 23
	s_cselect_b32 s79, 32, s32
	s_cselect_b32 s19, s61, s19
	s_lshl_b32 s32, s32, s11
	s_lshl_b32 s19, s19, 12
	s_add_u32 s32, s32, s19
	s_add_u32 s56, s56, s32
	s_addc_u32 s57, s57, 0
	s_add_i32 s79, s79, s10
	s_mul_i32 s79, s79, 0x3000
	v_readlane_b32 s19, v253, 21
	v_readlane_b32 s32, v253, 22
	s_nop 0
	s_add_u32 s50, s19, s79
	s_addc_u32 s51, s32, 0
	s_add_u32 s52, s50, 0x1000
	s_addc_u32 s53, s51, 0
	global_load_dwordx4 v[136:139], v156, s[56:57]
	global_load_dwordx4 v[140:143], v156, s[56:57] offset:1024
	global_load_dwordx4 v[144:147], v156, s[56:57] offset:2048
	global_load_dwordx4 v[148:151], v156, s[56:57] offset:3072
	global_load_dwordx4 v[216:219], v156, s[52:53]
	global_load_dwordx4 v[158:161], v156, s[50:51]
	global_load_dwordx4 v[220:223], v156, s[52:53] offset:1024
	global_load_dwordx4 v[162:165], v156, s[50:51] offset:1024
	global_load_dwordx4 v[224:227], v156, s[52:53] offset:2048
	global_load_dwordx4 v[166:169], v156, s[50:51] offset:2048
	global_load_dwordx4 v[228:231], v156, s[52:53] offset:3072
	global_load_dwordx4 v[170:173], v156, s[50:51] offset:3072
	v_readlane_b32 s19, v253, 2
	v_readlane_b32 s32, v255, 27
	s_nop 0
	s_add_i32 s18, s18, s19
	s_add_i32 s15, s15, s32
.Lp0_skipB_1:
	s_cmp_lg_u32 s45, 0
	s_cbranch_scc0 .Lp0_w0
	s_waitcnt vmcnt(12)
	s_branch .Lp0_x0

; DEV void norm_item(const Params& p, int l, int g, int item, int tid) {
;     ...
;   float4 v[4];
;   float ss = 0.f;
; #pragma unroll
;   for (int i = 0; i < 4; ++i) {
;     v[i] = *(const float4*)(src + i * 256 + lane * 4);
;     ss += v[i].x * v[i].x + v[i].y * v[i].y + v[i].z * v[i].z + v[i].w * v[i].w;
;   }
;   ss = wsum(ss, lane);
;   const float rstd = rsqrtf(ss * (1.f / D) + 1e-6f);
; #pragma unroll
;   for (int i = 0; i < 4; ++i) {
;     int col = i * 256 + lane * 4;
;     float4 gg = *(const float4*)(ng + col);
;     float4 sh = *(const float4*)(md + col);
;     float4 sc = *(const float4*)(md + 1024 + col);
;     uint2 o;
;     o.x = pack2(v[i].x * rstd * gg.x * (1.f + sc.x) + sh.x, v[i].y * rstd * gg.y * (1.f + sc.y) + sh.y);
;     o.y = pack2(v[i].z * rstd * gg.z * (1.f + sc.z) + sh.z, v[i].w * rstd * gg.w * (1.f + sc.w) + sh.w);
;     *(uint2*)(p.u + (long)r * D + col) = o;
;   }
.Lp0_x0:
.Lp0_loop:
	v_mov_b32_e32 v40, v5
	v_mov_b32_e32 v41, v9
	v_mov_b32_e32 v38, v4
	v_mov_b32_e32 v39, v8
	v_mov_b32_e32 v48, v13
	v_mov_b32_e32 v49, v17
	v_pk_mul_f32 v[40:41], v[40:41], v[40:41]
	v_mov_b32_e32 v2, v6
	v_mov_b32_e32 v3, v10
	v_mov_b32_e32 v46, v12
	v_mov_b32_e32 v47, v16
	v_pk_mul_f32 v[48:49], v[48:49], v[48:49]
	v_pk_fma_f32 v[38:39], v[38:39], v[38:39], v[40:41]
	v_mov_b32_e32 v36, v7
	v_mov_b32_e32 v37, v11
	v_mov_b32_e32 v42, v14
	v_mov_b32_e32 v43, v18
	v_pk_fma_f32 v[40:41], v[46:47], v[46:47], v[48:49]
	v_pk_fma_f32 v[2:3], v[2:3], v[2:3], v[38:39]
	v_mov_b32_e32 v44, v15
	v_mov_b32_e32 v45, v19
	v_pk_fma_f32 v[38:39], v[42:43], v[42:43], v[40:41]
	v_pk_fma_f32 v[2:3], v[36:37], v[36:37], v[2:3]
	v_pk_fma_f32 v[36:37], v[44:45], v[44:45], v[38:39]
	v_add_f32_e32 v2, v2, v3
	v_add_f32_e32 v2, v2, v36
	v_add_f32_e32 v2, v2, v37
	ds_bpermute_b32 v1, v64, v2
	s_waitcnt lgkmcnt(0)
	v_add_f32_e32 v1, v2, v1
	ds_bpermute_b32 v2, v65, v1
	s_waitcnt lgkmcnt(0)
	v_add_f32_e32 v1, v1, v2
	ds_bpermute_b32 v2, v66, v1
	s_waitcnt lgkmcnt(0)
	v_add_f32_e32 v2, v1, v2
	ds_bpermute_b32 v3, v67, v2
	s_waitcnt lgkmcnt(0)
	v_add_f32_e32 v2, v2, v3
	ds_bpermute_b32 v36, v68, v2
	s_waitcnt lgkmcnt(0)
	v_add_f32_e32 v40, v2, v36
	ds_bpermute_b32 v41, v69, v40
	s_waitcnt lgkmcnt(0)
	v_add_f32_e32 v0, v40, v41
	v_fmamk_f32 v0, v0, 0x3a800000, v196
	v_mul_f32_e32 v1, 0x4b800000, v0
	v_cmp_gt_f32_e32 vcc, s46, v0
	s_nop 1
	v_cndmask_b32_e32 v0, v0, v1, vcc
	v_rsq_f32_e32 v40, v0
	s_nop 0
	v_mul_f32_e32 v20, 0x45800000, v40
	v_cndmask_b32_e32 v40, v40, v20, vcc
	v_pk_add_f32 v[22:23], v[202:203], 1.0 op_sel_hi:[1,0]
	v_pk_add_f32 v[20:21], v[200:201], 1.0 op_sel_hi:[1,0]
	v_pk_mul_f32 v[24:25], v[4:5], v[40:41] op_sel_hi:[1,0]
	v_pk_mul_f32 v[26:27], v[6:7], v[40:41] op_sel_hi:[1,0]
	v_pk_mul_f32 v[24:25], v[96:97], v[24:25]
	v_pk_mul_f32 v[26:27], v[98:99], v[26:27]
	v_pk_fma_f32 v[20:21], v[20:21], v[24:25], v[174:175]
	v_pk_fma_f32 v[22:23], v[22:23], v[26:27], v[176:177]
	v_cvt_pk_bf16_f32 v70, v20, v21
	v_cvt_pk_bf16_f32 v71, v22, v23
	global_store_dwordx2 v50, v[70:71], s[12:13]
	v_pk_mul_f32 v[24:25], v[8:9], v[40:41] op_sel_hi:[1,0]
	v_pk_mul_f32 v[26:27], v[10:11], v[40:41] op_sel_hi:[1,0]
	v_pk_mul_f32 v[24:25], v[24:25], v[100:101]
	v_pk_mul_f32 v[26:27], v[26:27], v[102:103]
	v_pk_add_f32 v[20:21], v[204:205], 1.0 op_sel_hi:[1,0]
	v_pk_add_f32 v[22:23], v[206:207], 1.0 op_sel_hi:[1,0]
	v_pk_fma_f32 v[20:21], v[24:25], v[20:21], v[178:179]
	v_pk_fma_f32 v[22:23], v[26:27], v[22:23], v[180:181]
	v_cvt_pk_bf16_f32 v72, v20, v21
	v_cvt_pk_bf16_f32 v73, v22, v23
	global_store_dwordx2 v50, v[72:73], s[12:13] offset:512
	v_pk_mul_f32 v[24:25], v[12:13], v[40:41] op_sel_hi:[1,0]
	v_pk_mul_f32 v[26:27], v[14:15], v[40:41] op_sel_hi:[1,0]
	v_pk_mul_f32 v[24:25], v[24:25], v[104:105]
	v_pk_mul_f32 v[26:27], v[26:27], v[106:107]
	v_pk_add_f32 v[20:21], v[208:209], 1.0 op_sel_hi:[1,0]
	v_pk_add_f32 v[22:23], v[210:211], 1.0 op_sel_hi:[1,0]
	v_pk_fma_f32 v[20:21], v[24:25], v[20:21], v[182:183]
	v_pk_fma_f32 v[22:23], v[26:27], v[22:23], v[184:185]
	v_cvt_pk_bf16_f32 v74, v20, v21
	v_cvt_pk_bf16_f32 v75, v22, v23
	global_store_dwordx2 v50, v[74:75], s[12:13] offset:1024
	v_pk_mul_f32 v[24:25], v[16:17], v[40:41] op_sel_hi:[1,0]
	v_pk_mul_f32 v[26:27], v[18:19], v[40:41] op_sel_hi:[1,0]
	v_pk_mul_f32 v[24:25], v[24:25], v[108:109]
	v_pk_mul_f32 v[26:27], v[26:27], v[110:111]
	v_pk_add_f32 v[20:21], v[212:213], 1.0 op_sel_hi:[1,0]
	v_pk_add_f32 v[22:23], v[214:215], 1.0 op_sel_hi:[1,0]
	v_pk_fma_f32 v[20:21], v[24:25], v[20:21], v[186:187]
	v_pk_fma_f32 v[22:23], v[26:27], v[22:23], v[188:189]
	v_cvt_pk_bf16_f32 v76, v20, v21
	v_cvt_pk_bf16_f32 v77, v22, v23
	global_store_dwordx2 v50, v[76:77], s[12:13] offset:1536
	s_cmp_lg_u32 s45, 0
	s_cbranch_scc0 .Lp0_done
	s_mov_b32 s44, 0
	s_cmpk_gt_i32 s18, 0x8ff
	s_cbranch_scc1 .Lp0_skipA_2
	s_mov_b32 s44, 1
	s_add_i32 s19, s15, s60
	s_mul_hi_u32 s32, s19, 0x38e38e39
	s_lshr_b32 s32, s32, 9
	s_mul_i32 s11, s32, 0x900
	s_sub_i32 s61, s19, s11
	s_lshl_b32 s12, s19, 11
	s_add_u32 s12, s86, s12
	s_addc_u32 s13, s87, 0
	v_readlane_b32 s19, v255, 29
	s_nop 0
	s_add_i32 s32, s32, s19
	s_add_i32 s19, s61, 0xffffff00
	s_cmp_lt_u32 s61, 0x100
	s_cselect_b32 s62, s58, s48
	s_cselect_b32 s63, s59, s49
	s_cselect_b32 s11, 20, 23
	s_cselect_b32 s79, 32, s32
	s_cselect_b32 s19, s61, s19
	s_lshl_b32 s32, s32, s11
	s_lshl_b32 s19, s19, 12
	s_add_u32 s32, s32, s19
	s_add_u32 s62, s62, s32
	s_addc_u32 s63, s63, 0
	s_add_i32 s79, s79, s10
	s_mul_i32 s79, s79, 0x3000
	v_readlane_b32 s19, v253, 21
	v_readlane_b32 s32, v253, 22
	s_nop 0
	s_add_u32 s6, s19, s79
	s_addc_u32 s7, s32, 0
	s_add_u32 s8, s6, 0x1000
	s_addc_u32 s9, s7, 0
	global_load_dwordx4 v[4:7], v156, s[62:63]
	global_load_dwordx4 v[8:11], v156, s[62:63] offset:1024
	global_load_dwordx4 v[12:15], v156, s[62:63] offset:2048
	global_load_dwordx4 v[16:19], v156, s[62:63] offset:3072
	global_load_dwordx4 v[200:203], v156, s[8:9]
	global_load_dwordx4 v[174:177], v156, s[6:7]
	global_load_dwordx4 v[204:207], v156, s[8:9] offset:1024
	global_load_dwordx4 v[178:181], v156, s[6:7] offset:1024
	global_load_dwordx4 v[208:211], v156, s[8:9] offset:2048
	global_load_dwordx4 v[182:185], v156, s[6:7] offset:2048
	global_load_dwordx4 v[212:215], v156, s[8:9] offset:3072
	global_load_dwordx4 v[186:189], v156, s[6:7] offset:3072
	v_readlane_b32 s19, v253, 2
	v_readlane_b32 s32, v255, 27
	s_nop 0
	s_add_i32 s18, s18, s19
	s_add_i32 s15, s15, s32
.Lp0_skipA_2:
	s_cmp_lg_u32 s44, 0
	s_cbranch_scc0 .Lp0_w1
	s_waitcnt vmcnt(16)
	s_branch .Lp0_x1

; DEV void norm_item(const Params& p, int l, int g, int item, int tid) {
;     ...
;   float4 v[4];
;   float ss = 0.f;
; #pragma unroll
;   for (int i = 0; i < 4; ++i) {
;     v[i] = *(const float4*)(src + i * 256 + lane * 4);
;     ss += v[i].x * v[i].x + v[i].y * v[i].y + v[i].z * v[i].z + v[i].w * v[i].w;
;   }
;   ss = wsum(ss, lane);
;   const float rstd = rsqrtf(ss * (1.f / D) + 1e-6f);
; #pragma unroll
;   for (int i = 0; i < 4; ++i) {
;     int col = i * 256 + lane * 4;
;     float4 gg = *(const float4*)(ng + col);
;     float4 sh = *(const float4*)(md + col);
;     float4 sc = *(const float4*)(md + 1024 + col);
;     uint2 o;
;     o.x = pack2(v[i].x * rstd * gg.x * (1.f + sc.x) + sh.x, v[i].y * rstd * gg.y * (1.f + sc.y) + sh.y);
;     o.y = pack2(v[i].z * rstd * gg.z * (1.f + sc.z) + sh.z, v[i].w * rstd * gg.w * (1.f + sc.w) + sh.w);
;     *(uint2*)(p.u + (long)r * D + col) = o;
;   }
.Lp0_x1:
	v_mov_b32_e32 v40, v137
	v_mov_b32_e32 v41, v141
	v_mov_b32_e32 v38, v136
	v_mov_b32_e32 v39, v140
	v_mov_b32_e32 v48, v145
	v_mov_b32_e32 v49, v149
	v_pk_mul_f32 v[40:41], v[40:41], v[40:41]
	v_mov_b32_e32 v2, v138
	v_mov_b32_e32 v3, v142
	v_mov_b32_e32 v46, v144
	v_mov_b32_e32 v47, v148
	v_pk_mul_f32 v[48:49], v[48:49], v[48:49]
	v_pk_fma_f32 v[38:39], v[38:39], v[38:39], v[40:41]
	v_mov_b32_e32 v36, v139
	v_mov_b32_e32 v37, v143
	v_mov_b32_e32 v42, v146
	v_mov_b32_e32 v43, v150
	v_pk_fma_f32 v[40:41], v[46:47], v[46:47], v[48:49]
	v_pk_fma_f32 v[2:3], v[2:3], v[2:3], v[38:39]
	v_mov_b32_e32 v44, v147
	v_mov_b32_e32 v45, v151
	v_pk_fma_f32 v[38:39], v[42:43], v[42:43], v[40:41]
	v_pk_fma_f32 v[2:3], v[36:37], v[36:37], v[2:3]
	v_pk_fma_f32 v[36:37], v[44:45], v[44:45], v[38:39]
	v_add_f32_e32 v2, v2, v3
	v_add_f32_e32 v2, v2, v36
	v_add_f32_e32 v2, v2, v37
	ds_bpermute_b32 v1, v64, v2
	s_waitcnt lgkmcnt(0)
	v_add_f32_e32 v1, v2, v1
	ds_bpermute_b32 v2, v65, v1
	s_waitcnt lgkmcnt(0)
	v_add_f32_e32 v1, v1, v2
	ds_bpermute_b32 v2, v66, v1
	s_waitcnt lgkmcnt(0)
	v_add_f32_e32 v2, v1, v2
	ds_bpermute_b32 v3, v67, v2
	s_waitcnt lgkmcnt(0)
	v_add_f32_e32 v2, v2, v3
	ds_bpermute_b32 v36, v68, v2
	s_waitcnt lgkmcnt(0)
	v_add_f32_e32 v40, v2, v36
	ds_bpermute_b32 v41, v69, v40
	s_waitcnt lgkmcnt(0)
	v_add_f32_e32 v0, v40, v41
	v_fmamk_f32 v0, v0, 0x3a800000, v196
	v_mul_f32_e32 v1, 0x4b800000, v0
	v_cmp_gt_f32_e32 vcc, s46, v0
	s_nop 1
	v_cndmask_b32_e32 v0, v0, v1, vcc
	v_rsq_f32_e32 v40, v0
	s_nop 0
	v_mul_f32_e32 v20, 0x45800000, v40
	v_cndmask_b32_e32 v40, v40, v20, vcc
	v_pk_add_f32 v[22:23], v[218:219], 1.0 op_sel_hi:[1,0]
	v_pk_add_f32 v[20:21], v[216:217], 1.0 op_sel_hi:[1,0]
	v_pk_mul_f32 v[24:25], v[136:137], v[40:41] op_sel_hi:[1,0]
	v_pk_mul_f32 v[26:27], v[138:139], v[40:41] op_sel_hi:[1,0]
	v_pk_mul_f32 v[24:25], v[96:97], v[24:25]
	v_pk_mul_f32 v[26:27], v[98:99], v[26:27]
	v_pk_fma_f32 v[20:21], v[20:21], v[24:25], v[158:159]
	v_pk_fma_f32 v[22:23], v[22:23], v[26:27], v[160:161]
	v_cvt_pk_bf16_f32 v70, v20, v21
	v_cvt_pk_bf16_f32 v71, v22, v23
	global_store_dwordx2 v50, v[70:71], s[54:55]
	v_pk_mul_f32 v[24:25], v[140:141], v[40:41] op_sel_hi:[1,0]
	v_pk_mul_f32 v[26:27], v[142:143], v[40:41] op_sel_hi:[1,0]
	v_pk_mul_f32 v[24:25], v[24:25], v[100:101]
	v_pk_mul_f32 v[26:27], v[26:27], v[102:103]
	v_pk_add_f32 v[20:21], v[220:221], 1.0 op_sel_hi:[1,0]
	v_pk_add_f32 v[22:23], v[222:223], 1.0 op_sel_hi:[1,0]
	v_pk_fma_f32 v[20:21], v[24:25], v[20:21], v[162:163]
	v_pk_fma_f32 v[22:23], v[26:27], v[22:23], v[164:165]
	v_cvt_pk_bf16_f32 v72, v20, v21
	v_cvt_pk_bf16_f32 v73, v22, v23
	global_store_dwordx2 v50, v[72:73], s[54:55] offset:512
	v_pk_mul_f32 v[24:25], v[144:145], v[40:41] op_sel_hi:[1,0]
	v_pk_mul_f32 v[26:27], v[146:147], v[40:41] op_sel_hi:[1,0]
	v_pk_mul_f32 v[24:25], v[24:25], v[104:105]
	v_pk_mul_f32 v[26:27], v[26:27], v[106:107]
	v_pk_add_f32 v[20:21], v[224:225], 1.0 op_sel_hi:[1,0]
	v_pk_add_f32 v[22:23], v[226:227], 1.0 op_sel_hi:[1,0]
	v_pk_fma_f32 v[20:21], v[24:25], v[20:21], v[166:167]
	v_pk_fma_f32 v[22:23], v[26:27], v[22:23], v[168:169]
	v_cvt_pk_bf16_f32 v74, v20, v21
	v_cvt_pk_bf16_f32 v75, v22, v23
	global_store_dwordx2 v50, v[74:75], s[54:55] offset:1024
	v_pk_mul_f32 v[24:25], v[148:149], v[40:41] op_sel_hi:[1,0]
	v_pk_mul_f32 v[26:27], v[150:151], v[40:41] op_sel_hi:[1,0]
	v_pk_mul_f32 v[24:25], v[24:25], v[108:109]
	v_pk_mul_f32 v[26:27], v[26:27], v[110:111]
	v_pk_add_f32 v[20:21], v[228:229], 1.0 op_sel_hi:[1,0]
	v_pk_add_f32 v[22:23], v[230:231], 1.0 op_sel_hi:[1,0]
	v_pk_fma_f32 v[20:21], v[24:25], v[20:21], v[170:171]
	v_pk_fma_f32 v[22:23], v[26:27], v[22:23], v[172:173]
	v_cvt_pk_bf16_f32 v76, v20, v21
	v_cvt_pk_bf16_f32 v77, v22, v23
	global_store_dwordx2 v50, v[76:77], s[54:55] offset:1536
	s_cmp_lg_u32 s44, 0
	s_cbranch_scc0 .Lp0_done
	s_mov_b32 s45, 0
	s_cmpk_gt_i32 s18, 0x8ff
	s_cbranch_scc1 .Lp0_skipB_3
	s_mov_b32 s45, 1
	s_add_i32 s19, s15, s60
	s_mul_hi_u32 s32, s19, 0x38e38e39
	s_lshr_b32 s32, s32, 9
	s_mul_i32 s11, s32, 0x900
	s_sub_i32 s61, s19, s11
	s_lshl_b32 s54, s19, 11
	s_add_u32 s54, s86, s54
	s_addc_u32 s55, s87, 0
	v_readlane_b32 s19, v255, 29
	s_nop 0
	s_add_i32 s32, s32, s19
	s_add_i32 s19, s61, 0xffffff00
	s_cmp_lt_u32 s61, 0x100
	s_cselect_b32 s56, s58, s48
	s_cselect_b32 s57, s59, s49
	s_cselect_b32 s11, 20, 23
	s_cselect_b32 s79, 32, s32
	s_cselect_b32 s19, s61, s19
	s_lshl_b32 s32, s32, s11
	s_lshl_b32 s19, s19, 12
	s_add_u32 s32, s32, s19
	s_add_u32 s56, s56, s32
	s_addc_u32 s57, s57, 0
	s_add_i32 s79, s79, s10
	s_mul_i32 s79, s79, 0x3000
	v_readlane_b32 s19, v253, 21
	v_readlane_b32 s32, v253, 22
	s_nop 0
	s_add_u32 s50, s19, s79
	s_addc_u32 s51, s32, 0
	s_add_u32 s52, s50, 0x1000
	s_addc_u32 s53, s51, 0
	global_load_dwordx4 v[136:139], v156, s[56:57]
	global_load_dwordx4 v[140:143], v156, s[56:57] offset:1024
	global_load_dwordx4 v[144:147], v156, s[56:57] offset:2048
	global_load_dwordx4 v[148:151], v156, s[56:57] offset:3072
	global_load_dwordx4 v[216:219], v156, s[52:53]
	global_load_dwordx4 v[158:161], v156, s[50:51]
	global_load_dwordx4 v[220:223], v156, s[52:53] offset:1024
	global_load_dwordx4 v[162:165], v156, s[50:51] offset:1024
	global_load_dwordx4 v[224:227], v156, s[52:53] offset:2048
	global_load_dwordx4 v[166:169], v156, s[50:51] offset:2048
	global_load_dwordx4 v[228:231], v156, s[52:53] offset:3072
	global_load_dwordx4 v[170:173], v156, s[50:51] offset:3072
	v_readlane_b32 s19, v253, 2
	v_readlane_b32 s32, v255, 27
	s_nop 0
	s_add_i32 s18, s18, s19
	s_add_i32 s15, s15, s32
.Lp0_skipB_3:
	s_cmp_lg_u32 s45, 0
	s_cbranch_scc0 .Lp0_w2
	s_waitcnt vmcnt(16)
	s_branch .Lp0_x2
.Lp0_w2:
	s_waitcnt vmcnt(4)
